# gMLP prompt item: waves 4-7 delayed by s_sleep 6 after the staging barrier of each head (stagger against lockstep), on top of the S5 output-stage stagger
# speedup vs baseline: 1.0034x; 1.0034x over previous
; #define GAS __attribute__((address_space(1)))
; #define LAS __attribute__((address_space(3)))
; __device__ __forceinline__ void gmlp_prompt_item(LAS unsigned char* lds, int tid, int lane, int wave, size_t row0, const bf16* VG, const bf16* UG, const float* VST, ...
;     ...
;         bf16x8 bw[12]; float wsv[8];
;         unsigned wlo = (unsigned)(fr * 128 + 8 * fq) * 2u, slo = (unsigned)fr * 4u; asm volatile("" : "+v"(wlo), "+v"(slo));
;         const GAS char* wbase = (const GAS char*)(wsm + (size_t)h * 128 * 128); const GAS char* sbase = (const GAS char*)(wsums + h * 128);
;         { int idx_ = 0;
; #pragma unroll
;           for (int tb = 0; tb < 8; ++tb) {
; #pragma unroll
;               for (int ks = 0; ks <= (tb >> 1); ++ks) if (tb < 6) bw[idx_++] = *(const GAS bf16x8*)(wbase + (tb * 16 * 128 + ks * 32) * 2 + wlo);
;               wsv[tb] = *(const GAS float*)(sbase + tb * 64 + slo); } }
;         const f32x4 gc = *(const GAS f32x4*)(g_v + h * 128 + 16 * wave + 4 * fq), bc = *(const GAS f32x4*)(b_v + h * 128 + 16 * wave + 4 * fq);
;         __syncthreads();
;         bf16x8 a[4];
; #pragma unroll
;         for (int ks = 0; ks < 4; ++ks) a[ks] = *(const LAS bf16x8*)(vT + (16 * wave + fr) * 136 + 32 * ks + 8 * fq);
;         f32x4 accs[8];
;         { int idx_ = 0;
; #pragma unroll
;           for (int tb = 0; tb < 6; ++tb) { accs[tb] = (f32x4){0.f, 0.f, 0.f, 0.f};
; #pragma unroll
;               for (int ks = 0; ks <= (tb >> 1); ++ks) accs[tb] = __builtin_amdgcn_mfma_f32_16x16x32_bf16(a[ks], bw[idx_++], accs[tb], 0, 0, 0); } }
;         __builtin_amdgcn_sched_barrier(0);
;         bf16x8 bw2[8];
; #pragma unroll
;         for (int tb = 6; tb < 8; ++tb)
; #pragma unroll
;             for (int ks = 0; ks < 4; ++ks) bw2[(tb - 6) * 4 + ks] = *(const GAS bf16x8*)(wbase + (tb * 16 * 128 + ks * 32) * 2 + wlo);
.LBB0_907:
	s_add_u32 s2, s16, s20
	v_lshlrev_b32_e32 v28, 2, v84
	v_mov_b32_e32 v2, v200
	s_addc_u32 s3, s17, s21
	v_mov_b32_e32 v29, v3
	v_lshl_add_u64 v[190:191], s[2:3], 0, v[2:3]
	s_mov_b32 s2, 0x7741000
	v_add_co_u32_e64 v20, s[2:3], s2, v190
	v_lshl_add_u64 v[24:25], v[148:149], 0, s[4:5]
	s_nop 0
	v_addc_co_u32_e64 v21, s[2:3], 0, v191, s[2:3]
	s_mov_b32 s2, 0x7743000
	global_load_dwordx4 v[36:39], v[20:21], off offset:-4096
	global_load_dwordx4 v[40:43], v[20:21], off
	v_add_co_u32_e64 v20, s[2:3], s2, v190
	s_nop 1
	v_addc_co_u32_e64 v21, s[2:3], 0, v191, s[2:3]
	s_mov_b32 s2, 0x7745000
	s_nop 0
	v_add_co_u32_e64 v30, s[2:3], s2, v190
	global_load_dwordx4 v[44:47], v[20:21], off offset:-4096
	global_load_dwordx4 v[48:51], v[20:21], off
	v_addc_co_u32_e64 v31, s[2:3], 0, v191, s[2:3]
	s_mov_b32 s2, 0x7742000
	s_nop 0
	v_add_co_u32_e64 v22, s[2:3], s2, v190
	global_load_dwordx4 v[52:55], v[30:31], off offset:-4096
	global_load_dwordx4 v[56:59], v[30:31], off
	v_addc_co_u32_e64 v23, s[2:3], 0, v191, s[2:3]
	s_mov_b32 s2, 0x7744000
	s_nop 0
	v_add_co_u32_e64 v32, s[2:3], s2, v190
	global_load_dwordx4 v[60:63], v[22:23], off offset:64
	global_load_dwordx4 v[64:67], v[20:21], off offset:64
	v_addc_co_u32_e64 v33, s[2:3], 0, v191, s[2:3]
	s_add_u32 s2, s16, s4
	s_addc_u32 s3, s17, s5
	v_lshl_add_u64 v[28:29], s[2:3], 0, v[28:29]
	s_mov_b32 s2, 0x78b0000
	v_add_co_u32_e64 v28, s[2:3], s2, v28
	v_lshl_add_u64 v[20:21], v[146:147], 0, s[4:5]
	s_nop 0
	v_addc_co_u32_e64 v29, s[2:3], 0, v29, s[2:3]
	global_load_dwordx4 v[68:71], v[32:33], off offset:64
	s_nop 0
	global_load_dwordx4 v[20:23], v[20:21], off
	s_nop 0
	global_load_dwordx4 v[72:75], v[30:31], off offset:64
	s_nop 0
	global_load_dwordx4 v[24:27], v[24:25], off
	s_nop 0
	global_load_dwordx4 v[76:79], v[32:33], off offset:128
	global_load_dwordx4 v[224:227], v[30:31], off offset:128
	global_load_dword v206, v[28:29], off
	global_load_dword v208, v[28:29], off offset:64
	global_load_dword v242, v[28:29], off offset:128
	global_load_dword v244, v[28:29], off offset:192
	global_load_dword v198, v[28:29], off offset:256
	global_load_dword v196, v[28:29], off offset:320
	global_load_dword v194, v[28:29], off offset:384
	global_load_dword v188, v[28:29], off offset:448
	s_waitcnt lgkmcnt(0)
	s_barrier
	v_readfirstlane_b32 s99, v192
	s_nop 3
	s_lshr_b32 s99, s99, 6
	s_cmp_lt_u32 s99, 4
	s_cbranch_scc1 .Lgm_stag
	s_sleep 6
.Lgm_stag:
	ds_read_b128 v[32:35], v205
	ds_read_b128 v[28:31], v205 offset:64
	s_waitcnt vmcnt(21) lgkmcnt(1)
	v_mfma_f32_16x16x32_bf16 v[228:231], v[32:35], v[36:39], 0
	s_waitcnt vmcnt(20)
	v_mfma_f32_16x16x32_bf16 v[232:235], v[32:35], v[40:43], 0
	s_waitcnt vmcnt(19)
	v_mfma_f32_16x16x32_bf16 v[36:39], v[32:35], v[44:47], 0
	s_waitcnt vmcnt(18)
	v_mfma_f32_16x16x32_bf16 v[40:43], v[32:35], v[48:51], 0
	s_waitcnt vmcnt(17)
	v_mfma_f32_16x16x32_bf16 v[44:47], v[32:35], v[52:55], 0
	s_waitcnt vmcnt(16)
	v_mfma_f32_16x16x32_bf16 v[48:51], v[32:35], v[56:59], 0
	s_waitcnt vmcnt(15) lgkmcnt(0)
	v_mfma_f32_16x16x32_bf16 v[248:251], v[28:31], v[60:63], v[36:39]
	s_waitcnt vmcnt(14)
	v_mfma_f32_16x16x32_bf16 v[238:241], v[28:31], v[64:67], v[40:43]
	s_nop 2
	ds_read_b128 v[40:43], v205 offset:128
	ds_read_b128 v[36:39], v205 offset:192
	s_waitcnt vmcnt(13)
	v_mfma_f32_16x16x32_bf16 v[44:47], v[28:31], v[68:71], v[44:47]
	s_waitcnt vmcnt(11)
	v_mfma_f32_16x16x32_bf16 v[48:51], v[28:31], v[72:75], v[48:51]
	s_waitcnt vmcnt(9) lgkmcnt(1)
	v_mfma_f32_16x16x32_bf16 v[80:83], v[40:43], v[76:79], v[44:47]
	s_waitcnt vmcnt(8)
	v_mfma_f32_16x16x32_bf16 v[76:79], v[40:43], v[224:227], v[48:51]
	s_mov_b32 s2, 0x7746000
	s_nop 0
	v_add_co_u32_e64 v44, s[2:3], s2, v190
	s_nop 1
	v_addc_co_u32_e64 v45, s[2:3], 0, v191, s[2:3]
	s_mov_b32 s2, 0x7747000
	s_nop 0
	v_add_co_u32_e64 v46, s[2:3], s2, v190
	s_nop 1
	v_addc_co_u32_e64 v47, s[2:3], 0, v191, s[2:3]
	global_load_dwordx4 v[68:71], v[44:45], off offset:64
	global_load_dwordx4 v[64:67], v[44:45], off offset:128
	global_load_dwordx4 v[72:75], v[46:47], off offset:-4096
	global_load_dwordx4 v[60:63], v[44:45], off offset:192
	global_load_dwordx4 v[56:59], v[46:47], off
	global_load_dwordx4 v[52:55], v[46:47], off offset:64
	global_load_dwordx4 v[48:51], v[46:47], off offset:128
	s_nop 0
	global_load_dwordx4 v[44:47], v[46:47], off offset:192
	v_mov_b32_e32 v207, v20
	v_mov_b32_e32 v190, v24
	v_mov_b32_e32 v191, v228
	s_waitcnt vmcnt(15)
	v_pk_mul_f32 v[212:213], v[206:207], v[190:191]
	v_mov_b32_e32 v207, v21
	v_mov_b32_e32 v228, v25
	v_pk_mul_f32 v[226:227], v[206:207], v[228:229]
	v_mov_b32_e32 v207, v22
	v_mov_b32_e32 v190, v26
	v_mov_b32_e32 v191, v230
	v_pk_mul_f32 v[228:229], v[206:207], v[190:191]
	v_mov_b32_e32 v207, v23
	v_mov_b32_e32 v230, v27
	v_pk_mul_f32 v[206:207], v[206:207], v[230:231]
	v_mov_b32_e32 v209, v20
	v_mov_b32_e32 v230, v24
	v_mov_b32_e32 v231, v232
	s_waitcnt vmcnt(14)
; #define GAS __attribute__((address_space(1)))
; __device__ __forceinline__ unsigned pk2(float lo, float hi) { unsigned r; asm("v_cvt_pk_bf16_f32 %0, %1, %2" : "=v"(r) : "v"(lo), "v"(hi)); return r; }
; __device__ __forceinline__ float bflo(unsigned w) { return __uint_as_float(w << 16); }
; __device__ __forceinline__ float bfhi(unsigned w) { return __uint_as_float(w & 0xffff0000u); }
; __device__ __forceinline__ void gmlp_prompt_item(LAS unsigned char* lds, int tid, int lane, int wave, size_t row0, const bf16* VG, const bf16* UG, const float* VST, ...
;     ...
;         for (int tb = 0; tb < 8; ++tb) {
;             if (tb >= 6) { accs[tb] = (f32x4){0.f, 0.f, 0.f, 0.f};
; #pragma unroll
;                 for (int ks = 0; ks < 4; ++ks) accs[tb] = __builtin_amdgcn_mfma_f32_16x16x32_bf16(a[ks], bw2[(tb - 6) * 4 + ks], accs[tb], 0, 0, 0); }
;             const f32x4 acc = accs[tb];
;             const int t = 16 * tb + fr;
;             const float wsum = wsv[tb];
;             f32x4 y; y[0] = bflo(uq[tb].x) * (gc[0] * acc[0] + bc[0] * wsum + bias[tb]); y[1] = bfhi(uq[tb].x) * (gc[1] * acc[1] + bc[1] * wsum + bias[tb]);
;             y[2] = bflo(uq[tb].y) * (gc[2] * acc[2] + bc[2] * wsum + bias[tb]); y[3] = bfhi(uq[tb].y) * (gc[3] * acc[3] + bc[3] * wsum + bias[tb]);
;             sq[tb] += (y[0] * y[0] + y[1] * y[1]) + (y[2] * y[2] + y[3] * y[3]);
;             v2u o; o.x = pk2(y[0], y[1]); o.y = pk2(y[2], y[3]);
;             *(GAS v2u*)(YCAT + (row0 + t) * DM + 512 + h * 128 + 16 * wave + 4 * fq) = o;
;         }
	v_pk_mul_f32 v[230:231], v[208:209], v[230:231]
	v_mov_b32_e32 v209, v21
	v_mov_b32_e32 v232, v25
	v_pk_mul_f32 v[232:233], v[208:209], v[232:233]
	v_mov_b32_e32 v224, v212
	v_mov_b32_e32 v225, v230
	v_mov_b32_e32 v230, v213
	v_mov_b32_e32 v209, v22
	v_mov_b32_e32 v236, v26
	v_mov_b32_e32 v237, v234
	v_pk_add_f32 v[212:213], v[224:225], v[230:231]
	v_mov_b32_e32 v230, v226
	v_mov_b32_e32 v231, v232
	v_mov_b32_e32 v232, v227
	v_pk_mul_f32 v[236:237], v[208:209], v[236:237]
	v_mov_b32_e32 v209, v23
	v_mov_b32_e32 v234, v27
	v_pk_add_f32 v[226:227], v[230:231], v[232:233]
	v_pk_mul_f32 v[208:209], v[208:209], v[234:235]
	v_and_b32_e32 v225, 0xffff0000, v184
	v_and_b32_e32 v224, 0xffff0000, v182
	v_pk_add_f32 v[226:227], v[186:187], v[226:227]
	v_lshlrev_b32_e32 v235, 16, v184
	v_lshlrev_b32_e32 v234, 16, v182
	v_pk_mul_f32 v[224:225], v[226:227], v[224:225]
	v_lshlrev_b32_e32 v226, 16, v183
	v_and_b32_e32 v184, 0xffff0000, v183
	v_mov_b32_e32 v182, v206
	v_mov_b32_e32 v183, v208
	v_mov_b32_e32 v208, v207
	v_mov_b32_e32 v230, v228
	v_mov_b32_e32 v231, v236
	v_mov_b32_e32 v236, v229
	v_pk_add_f32 v[182:183], v[182:183], v[208:209]
	v_lshlrev_b32_e32 v227, 16, v185
	v_pk_add_f32 v[228:229], v[230:231], v[236:237]
	v_and_b32_e32 v185, 0xffff0000, v185
	v_pk_add_f32 v[182:183], v[186:187], v[182:183]
	v_lshl_add_u64 v[190:191], s[16:17], 0, v[142:143]
	v_pk_add_f32 v[212:213], v[186:187], v[212:213]
	v_pk_add_f32 v[228:229], v[186:187], v[228:229]
	v_pk_mul_f32 v[182:183], v[182:183], v[184:185]
	s_mov_b32 s2, 0xbc00000
	v_pk_mul_f32 v[212:213], v[212:213], v[234:235]
	v_pk_mul_f32 v[226:227], v[228:229], v[226:227]
	v_pk_mul_f32 v[184:185], v[224:225], v[224:225]
	v_pk_mul_f32 v[186:187], v[182:183], v[182:183]
	v_add_co_u32_e64 v206, s[2:3], s2, v190
	v_pk_fma_f32 v[184:185], v[212:213], v[212:213], v[184:185]
	v_pk_fma_f32 v[186:187], v[226:227], v[226:227], v[186:187]
	v_addc_co_u32_e64 v207, s[2:3], 0, v191, s[2:3]
	v_pk_add_f32 v[184:185], v[184:185], v[186:187]
	s_mov_b32 s2, 0xbc08000
	v_pk_add_f32 v[122:123], v[122:123], v[184:185]
	v_add_co_u32_e64 v184, s[2:3], s2, v190
	v_cvt_pk_bf16_f32 v187, v226, v182
	v_cvt_pk_bf16_f32 v182, v213, v225
	v_cvt_pk_bf16_f32 v183, v227, v183
	v_mov_b32_e32 v243, v20
	s_nop 0
	v_addc_co_u32_e64 v185, s[2:3], 0, v191, s[2:3]
	global_store_dwordx2 v[184:185], v[182:183], off offset:1024
	v_mov_b32_e32 v182, v24
	v_mov_b32_e32 v183, v248
	v_mov_b32_e32 v245, v20
	v_mov_b32_e32 v208, v24
	v_mov_b32_e32 v209, v238
	s_waitcnt vmcnt(14)
	v_pk_mul_f32 v[182:183], v[242:243], v[182:183]
	s_waitcnt vmcnt(13)
	v_pk_mul_f32 v[208:209], v[244:245], v[208:209]
	v_mov_b32_e32 v230, v182
	v_mov_b32_e32 v231, v208
	v_mov_b32_e32 v208, v183
	s_waitcnt vmcnt(6)
	v_mfma_f32_16x16x32_bf16 v[72:75], v[32:35], v[72:75], 0
	v_mov_b32_e32 v243, v21
	v_mov_b32_e32 v248, v25
	v_mov_b32_e32 v245, v21
	v_mov_b32_e32 v238, v25
	v_pk_add_f32 v[182:183], v[230:231], v[208:209]
	v_cvt_pk_bf16_f32 v186, v212, v224
	v_pk_mul_f32 v[184:185], v[242:243], v[248:249]
	v_pk_mul_f32 v[212:213], v[244:245], v[238:239]
	v_lshlrev_b32_e32 v229, 16, v178
	v_lshlrev_b32_e32 v228, 16, v176
	v_pk_add_f32 v[182:183], v[180:181], v[182:183]
	global_store_dwordx2 v[206:207], v[186:187], off offset:1024
	v_mov_b32_e32 v243, v22
	v_mov_b32_e32 v186, v26
	v_mov_b32_e32 v187, v250
	v_mov_b32_e32 v245, v22
	v_mov_b32_e32 v224, v26
	v_mov_b32_e32 v225, v240
	v_pk_mul_f32 v[182:183], v[182:183], v[228:229]
	v_mov_b32_e32 v228, v184
	v_mov_b32_e32 v229, v212
	v_mov_b32_e32 v212, v185
	v_pk_mul_f32 v[186:187], v[242:243], v[186:187]
	v_mov_b32_e32 v243, v23
	v_mov_b32_e32 v250, v27
	v_pk_mul_f32 v[224:225], v[244:245], v[224:225]
	v_mov_b32_e32 v245, v23
	v_mov_b32_e32 v240, v27
	v_pk_add_f32 v[184:185], v[228:229], v[212:213]
	v_mfma_f32_16x16x32_bf16 v[68:71], v[28:31], v[68:71], v[72:75]
	v_mul_f32_e64 v206, v242, v250
	v_mul_f32_e64 v207, v243, v251
	v_pk_mul_f32 v[226:227], v[244:245], v[240:241]
	v_and_b32_e32 v209, 0xffff0000, v178
	v_and_b32_e32 v208, 0xffff0000, v176
	v_pk_add_f32 v[184:185], v[180:181], v[184:185]
	v_and_b32_e32 v178, 0xffff0000, v177
	v_pk_mul_f32 v[184:185], v[184:185], v[208:209]
	v_lshlrev_b32_e32 v208, 16, v177
	v_mov_b32_e32 v176, v206
	v_mov_b32_e32 v177, v226
	v_mov_b32_e32 v226, v207
	v_mov_b32_e32 v212, v186
	v_mov_b32_e32 v213, v224
	v_mov_b32_e32 v224, v187
	v_pk_add_f32 v[176:177], v[176:177], v[226:227]
	v_lshlrev_b32_e32 v209, 16, v179
	v_pk_add_f32 v[186:187], v[212:213], v[224:225]
	v_and_b32_e32 v179, 0xffff0000, v179
	v_pk_add_f32 v[176:177], v[180:181], v[176:177]
	v_mfma_f32_16x16x32_bf16 v[64:67], v[40:43], v[64:67], v[68:71]
	v_add_f32_e64 v186, v180, v186
	v_add_f32_e64 v187, v181, v187
	v_pk_mul_f32 v[176:177], v[176:177], v[178:179]
	v_pk_mul_f32 v[186:187], v[186:187], v[208:209]
	v_pk_mul_f32 v[178:179], v[184:185], v[184:185]
	v_pk_mul_f32 v[180:181], v[176:177], v[176:177]
	v_pk_fma_f32 v[178:179], v[182:183], v[182:183], v[178:179]
	v_pk_fma_f32 v[180:181], v[186:187], v[186:187], v[180:181]
	s_mov_b32 s2, 0xbc10000
	s_waitcnt vmcnt(5)
	v_mfma_f32_16x16x32_bf16 v[32:35], v[32:35], v[56:59], 0
	v_add_f32_e64 v178, v178, v180
	v_add_f32_e64 v179, v179, v181
	v_add_co_u32_e64 v206, s[2:3], s2, v190
	s_waitcnt lgkmcnt(0)
; #define GAS __attribute__((address_space(1)))
; __device__ __forceinline__ unsigned pk2(float lo, float hi) { unsigned r; asm("v_cvt_pk_bf16_f32 %0, %1, %2" : "=v"(r) : "v"(lo), "v"(hi)); return r; }
; __device__ __forceinline__ float bflo(unsigned w) { return __uint_as_float(w << 16); }
; __device__ __forceinline__ float bfhi(unsigned w) { return __uint_as_float(w & 0xffff0000u); }
; __device__ __forceinline__ void gmlp_prompt_item(LAS unsigned char* lds, int tid, int lane, int wave, size_t row0, const bf16* VG, const bf16* UG, const float* VST, ...
;     ...
;         for (int tb = 0; tb < 8; ++tb) {
;             if (tb >= 6) { accs[tb] = (f32x4){0.f, 0.f, 0.f, 0.f};
; #pragma unroll
;                 for (int ks = 0; ks < 4; ++ks) accs[tb] = __builtin_amdgcn_mfma_f32_16x16x32_bf16(a[ks], bw2[(tb - 6) * 4 + ks], accs[tb], 0, 0, 0); }
;             const f32x4 acc = accs[tb];
;             const int t = 16 * tb + fr;
;             const float wsum = wsv[tb];
;             f32x4 y; y[0] = bflo(uq[tb].x) * (gc[0] * acc[0] + bc[0] * wsum + bias[tb]); y[1] = bfhi(uq[tb].x) * (gc[1] * acc[1] + bc[1] * wsum + bias[tb]);
;             y[2] = bflo(uq[tb].y) * (gc[2] * acc[2] + bc[2] * wsum + bias[tb]); y[3] = bfhi(uq[tb].y) * (gc[3] * acc[3] + bc[3] * wsum + bias[tb]);
;             sq[tb] += (y[0] * y[0] + y[1] * y[1]) + (y[2] * y[2] + y[3] * y[3]);
;             v2u o; o.x = pk2(y[0], y[1]); o.y = pk2(y[2], y[3]);
;             *(GAS v2u*)(YCAT + (row0 + t) * DM + 512 + h * 128 + 16 * wave + 4 * fq) = o;
;         }
;         __syncthreads();
	v_mfma_f32_16x16x32_bf16 v[60:63], v[36:39], v[60:63], v[64:67]
	v_cvt_pk_bf16_f32 v180, v182, v184
	v_cvt_pk_bf16_f32 v181, v186, v176
	v_addc_co_u32_e64 v207, s[2:3], 0, v191, s[2:3]
	v_pk_add_f32 v[120:121], v[120:121], v[178:179]
	v_cvt_pk_bf16_f32 v176, v183, v185
	v_cvt_pk_bf16_f32 v177, v187, v177
	v_lshl_add_u64 v[178:179], s[16:17], 0, v[144:145]
	global_store_dwordx2 v[206:207], v[180:181], off offset:1024
	global_store_dwordx2 v[178:179], v[176:177], off
	v_mov_b32_e32 v199, v20
	v_mov_b32_e32 v176, v24
	v_mov_b32_e32 v177, v80
	v_mov_b32_e32 v197, v20
	v_mov_b32_e32 v180, v24
	v_mov_b32_e32 v181, v76
	v_pk_mul_f32 v[176:177], v[198:199], v[176:177]
	v_mov_b32_e32 v199, v21
	v_mov_b32_e32 v80, v25
	v_pk_mul_f32 v[180:181], v[196:197], v[180:181]
	v_mov_b32_e32 v197, v21
	v_mov_b32_e32 v76, v25
	s_waitcnt vmcnt(6)
	v_mfma_f32_16x16x32_bf16 v[28:31], v[28:31], v[52:55], v[32:35]
	v_mul_f32_e64 v80, v198, v80
	v_mul_f32_e64 v81, v199, v81
	v_mov_b32_e32 v199, v22
	v_mov_b32_e32 v178, v26
	v_mov_b32_e32 v179, v82
	v_pk_mul_f32 v[76:77], v[196:197], v[76:77]
	v_mov_b32_e32 v197, v22
	v_mov_b32_e32 v182, v26
	v_mov_b32_e32 v183, v78
	v_mov_b32_e32 v186, v176
	v_mov_b32_e32 v187, v180
	v_mov_b32_e32 v180, v177
	v_mov_b32_e32 v195, v20
	v_mov_b32_e32 v64, v24
	v_mov_b32_e32 v65, v60
	v_pk_mul_f32 v[178:179], v[198:199], v[178:179]
	v_mov_b32_e32 v199, v23
	v_mov_b32_e32 v82, v27
	v_pk_mul_f32 v[182:183], v[196:197], v[182:183]
	v_mov_b32_e32 v197, v23
	v_mov_b32_e32 v78, v27
	v_pk_add_f32 v[176:177], v[186:187], v[180:181]
	v_pk_mul_f32 v[64:65], v[194:195], v[64:65]
	v_pk_mul_f32 v[82:83], v[198:199], v[82:83]
	v_pk_mul_f32 v[78:79], v[196:197], v[78:79]
	v_lshlrev_b32_e32 v185, 16, v174
	v_lshlrev_b32_e32 v184, 16, v172
	v_pk_add_f32 v[176:177], v[170:171], v[176:177]
	v_add_f32_e32 v60, v64, v65
	v_pk_mul_f32 v[176:177], v[176:177], v[184:185]
	v_and_b32_e32 v181, 0xffff0000, v174
	v_and_b32_e32 v180, 0xffff0000, v172
	v_mov_b32_e32 v184, v80
	v_mov_b32_e32 v185, v76
	v_mov_b32_e32 v76, v81
	v_lshlrev_b32_e32 v80, 16, v173
	v_and_b32_e32 v174, 0xffff0000, v173
	v_mov_b32_e32 v172, v82
	v_mov_b32_e32 v173, v78
	v_mov_b32_e32 v78, v83
	s_mov_b32 s2, 0xbc20000
	v_add_f32_e32 v64, v189, v60
	v_mov_b32_e32 v195, v21
	v_mov_b32_e32 v60, v25
	s_waitcnt vmcnt(5)
	v_mfma_f32_16x16x32_bf16 v[28:31], v[40:43], v[48:51], v[28:31]
	v_add_f32_e64 v76, v184, v76
	v_add_f32_e64 v77, v185, v77
	v_pk_add_f32 v[78:79], v[172:173], v[78:79]
	v_add_co_u32_e64 v172, s[2:3], s2, v190
	v_pk_mul_f32 v[60:61], v[194:195], v[60:61]
	v_pk_add_f32 v[76:77], v[170:171], v[76:77]
	v_addc_co_u32_e64 v173, s[2:3], 0, v191, s[2:3]
	v_add_f32_e32 v60, v60, v61
	v_pk_mul_f32 v[76:77], v[76:77], v[180:181]
	v_mov_b32_e32 v180, v178
	v_mov_b32_e32 v181, v182
	v_mov_b32_e32 v182, v179
	s_mov_b32 s2, 0xbc28000
	v_add_f32_e32 v66, v189, v60
	v_mov_b32_e32 v195, v22
	v_mov_b32_e32 v60, v26
	v_mov_b32_e32 v61, v62
	v_pk_add_f32 v[178:179], v[180:181], v[182:183]
	v_add_co_u32_e64 v68, s[2:3], s2, v190
	v_pk_mul_f32 v[60:61], v[194:195], v[60:61]
	s_waitcnt vmcnt(4)
	v_mfma_f32_16x16x32_bf16 v[28:31], v[36:39], v[44:47], v[28:31]
	v_lshlrev_b32_e32 v81, 16, v175
	v_pk_add_f32 v[178:179], v[170:171], v[178:179]
	v_and_b32_e32 v175, 0xffff0000, v175
	v_pk_add_f32 v[78:79], v[170:171], v[78:79]
	v_addc_co_u32_e64 v69, s[2:3], 0, v191, s[2:3]
	v_add_f32_e32 v60, v60, v61
	v_mov_b32_e32 v195, v23
	v_mov_b32_e32 v62, v27
	v_pk_mul_f32 v[80:81], v[178:179], v[80:81]
	v_pk_mul_f32 v[78:79], v[78:79], v[174:175]
	v_cvt_pk_bf16_f32 v72, v177, v77
	v_mov_b32_e32 v36, v24
	v_cvt_pk_bf16_f32 v73, v81, v79
	global_store_dwordx2 v[68:69], v[72:73], off offset:1024
	v_add_f32_e32 v68, v189, v60
	v_pk_mul_f32 v[60:61], v[194:195], v[62:63]
	v_mov_b32_e32 v37, v28
	v_add_f32_e32 v60, v60, v61
	v_add_f32_e32 v62, v189, v60
	v_mov_b32_e32 v189, v20
	v_lshlrev_b32_e32 v2, 16, v168
	v_pk_mul_f32 v[36:37], v[188:189], v[36:37]
	v_mov_b32_e32 v20, v188
	v_mul_f32_e32 v32, v64, v2
	v_add_f32_e32 v2, v36, v37
	v_mov_b32_e32 v28, v25
	v_lshlrev_b32_e32 v63, 16, v166
	v_add_f32_e32 v2, v215, v2
	v_pk_mul_f32 v[20:21], v[20:21], v[28:29]
	v_mov_b32_e32 v60, v188
	v_mov_b32_e32 v61, v22
	v_mul_f32_e32 v33, v2, v63
	v_add_f32_e32 v2, v20, v21
	v_mov_b32_e32 v20, v26
	v_mov_b32_e32 v21, v30
	v_and_b32_e32 v70, 0xffff0000, v166
	v_add_f32_e32 v2, v215, v2
	v_pk_mul_f32 v[20:21], v[60:61], v[20:21]
	v_mov_b32_e32 v22, v188
	v_mul_f32_e32 v35, v2, v70
	v_add_f32_e32 v2, v20, v21
	v_mov_b32_e32 v30, v27
	v_lshlrev_b32_e32 v71, 16, v167
	v_add_f32_e32 v2, v215, v2
	v_pk_mul_f32 v[20:21], v[22:23], v[30:31]
	v_mul_f32_e32 v53, v2, v71
	v_add_f32_e32 v2, v20, v21
	v_and_b32_e32 v65, 0xffff0000, v168
	v_and_b32_e32 v69, 0xffff0000, v169
	v_and_b32_e32 v56, 0xffff0000, v167
	v_add_f32_e32 v2, v215, v2
	v_lshlrev_b32_e32 v67, 16, v169
	v_mul_f32_e32 v34, v66, v65
	v_mul_f32_e32 v40, v62, v69
	v_mul_f32_e32 v41, v2, v56
	v_mul_f32_e32 v52, v68, v67
	v_pk_mul_f32 v[20:21], v[34:35], v[34:35]
	v_pk_mul_f32 v[22:23], v[40:41], v[40:41]
	s_add_i32 s24, s24, -1
	v_pk_fma_f32 v[20:21], v[32:33], v[32:33], v[20:21]
	v_pk_fma_f32 v[22:23], v[52:53], v[52:53], v[22:23]
	s_mov_b32 s2, 0xbc30000
	s_add_u32 s4, s4, 0x200
	v_pk_mul_f32 v[82:83], v[76:77], v[76:77]
	v_pk_mul_f32 v[170:171], v[78:79], v[78:79]
	v_pk_add_f32 v[20:21], v[20:21], v[22:23]
	v_add_co_u32_e64 v22, s[2:3], s2, v190
	s_addc_u32 s5, s5, 0
	v_pk_fma_f32 v[82:83], v[176:177], v[176:177], v[82:83]
	v_pk_fma_f32 v[170:171], v[80:81], v[80:81], v[170:171]
	v_addc_co_u32_e64 v23, s[2:3], 0, v191, s[2:3]
	s_add_u32 s20, s20, 0x8000
	v_pk_add_f32 v[82:83], v[82:83], v[170:171]
	v_cvt_pk_bf16_f32 v170, v176, v76
	v_cvt_pk_bf16_f32 v171, v80, v78
	s_mov_b64 s[2:3], 0x100
	s_addc_u32 s21, s21, 0
	global_store_dwordx2 v[172:173], v[170:171], off offset:1024
	v_pk_add_f32 v[118:119], v[118:119], v[82:83]
	v_cvt_pk_bf16_f32 v42, v32, v34
	v_cvt_pk_bf16_f32 v43, v52, v40
	global_store_dwordx2 v[22:23], v[42:43], off offset:1024
	v_pk_add_f32 v[106:107], v[106:107], v[20:21]
	v_lshl_add_u64 v[22:23], s[16:17], 0, v[140:141]
	v_lshl_add_u64 v[140:141], v[140:141], 0, s[2:3]
	v_lshl_add_u64 v[142:143], v[142:143], 0, s[2:3]
	s_mov_b64 s[94:95], 0x100
	v_lshl_add_u64 v[144:145], v[144:145], 0, s[2:3]
	s_cmp_eq_u32 s24, 0
	v_mov_b32_e32 v189, v216
	v_mov_b32_e32 v215, v217
	v_mov_b64_e32 v[182:183], v[150:151]
	v_mov_b64_e32 v[184:185], v[152:153]
	v_mov_b64_e32 v[176:177], v[154:155]
	v_mov_b64_e32 v[178:179], v[156:157]
	v_mov_b64_e32 v[172:173], v[158:159]
	v_mov_b64_e32 v[174:175], v[160:161]
	v_mov_b64_e32 v[168:169], v[162:163]
	v_mov_b64_e32 v[166:167], v[164:165]
	v_mov_b32_e32 v186, v218
	v_mov_b32_e32 v187, v222
	v_mov_b32_e32 v180, v219
	v_mov_b32_e32 v181, v223
	v_mov_b32_e32 v170, v220
	v_mov_b32_e32 v171, v221
	v_cvt_pk_bf16_f32 v20, v33, v35
	v_cvt_pk_bf16_f32 v21, v53, v41
	global_store_dwordx2 v[22:23], v[20:21], off
	s_barrier
	s_cbranch_scc1 .LBB0_910
